# P4/P9 big-GEMM epilogue: the 16-byte bf16 stores re-mapped so adjacent lanes write contiguous bytes (data moved between lanes with ds_bpermute before each store)
# speedup vs baseline: 1.0052x; 1.0052x over previous
.LBB0_877:
	v_and_b32_e32 v238, 63, v204
	v_lshrrev_b32_e32 v176, 2, v238
	v_and_b32_e32 v222, 3, v238
	v_lshlrev_b32_e32 v225, 4, v222
	v_add_u32_e32 v225, v225, v176
	v_lshlrev_b32_e32 v225, 2, v225
	v_and_b32_e32 v223, 15, v238
	v_sub_u32_e32 v176, v176, v223
	v_lshlrev_b32_e32 v176, 13, v176
	v_bfe_u32 v223, v238, 4, 2
	v_sub_u32_e32 v222, v222, v223
	v_lshlrev_b32_e32 v222, 4, v222
	v_add_u32_e32 v222, v176, v222
	v_ashrrev_i32_e32 v223, 31, v222
	v_add_u32_e32 v160, 0x80, v140
	v_lshl_or_b32 v162, s50, 8, v151
	s_waitcnt lgkmcnt(0)
	v_pk_mul_f32 v[128:129], v[128:129], v[158:159] op_sel_hi:[1,0]
	v_pk_mul_f32 v[126:127], v[126:127], v[158:159] op_sel_hi:[1,0]
	v_pk_mul_f32 v[122:123], v[122:123], v[158:159] op_sel_hi:[1,0]
	v_max_f32_e32 v129, 0, v129
	v_max_f32_e32 v128, 0, v128
	v_max_f32_e32 v127, 0, v127
	v_max_f32_e32 v126, 0, v126
	v_pk_mul_f32 v[124:125], v[124:125], v[158:159] op_sel_hi:[1,0]
	v_max_f32_e32 v123, 0, v123
	v_max_f32_e32 v122, 0, v122
	v_lshlrev_b64 v[164:165], 13, v[140:141]
	v_max_f32_e32 v125, 0, v125
	v_max_f32_e32 v124, 0, v124
	v_pk_mul_f32 v[128:129], v[128:129], v[128:129]
	v_pk_mul_f32 v[126:127], v[126:127], v[126:127]
	v_pk_mul_f32 v[122:123], v[122:123], v[122:123]
	v_ashrrev_i32_e32 v163, 31, v162
	v_pk_mul_f32 v[166:167], v[124:125], v[124:125]
	v_cvt_pk_bf16_f32 v124, v126, v127
	v_cvt_pk_bf16_f32 v125, v128, v129
	v_cvt_pk_bf16_f32 v126, v122, v123
	v_lshl_add_u64 v[128:129], s[68:69], 0, v[164:165]
	v_lshlrev_b64 v[122:123], 1, v[162:163]
	v_pk_mul_f32 v[120:121], v[120:121], v[158:159] op_sel_hi:[1,0]
	v_pk_mul_f32 v[118:119], v[118:119], v[158:159] op_sel_hi:[1,0]
	v_pk_mul_f32 v[116:117], v[116:117], v[158:159] op_sel_hi:[1,0]
	v_pk_mul_f32 v[114:115], v[114:115], v[158:159] op_sel_hi:[1,0]
	v_cvt_pk_bf16_f32 v127, v166, v167
	v_lshl_add_u64 v[128:129], v[128:129], 0, v[122:123]
	v_max_f32_e32 v121, 0, v121
	v_max_f32_e32 v120, 0, v120
	v_max_f32_e32 v119, 0, v119
	v_max_f32_e32 v118, 0, v118
	v_max_f32_e32 v117, 0, v117
	v_max_f32_e32 v116, 0, v116
	v_max_f32_e32 v115, 0, v115
	v_max_f32_e32 v114, 0, v114
	v_lshl_add_u64 v[128:129], v[128:129], 0, v[222:223]
	ds_bpermute_b32 v124, v225, v124
	ds_bpermute_b32 v125, v225, v125
	ds_bpermute_b32 v126, v225, v126
	ds_bpermute_b32 v127, v225, v127
	s_waitcnt lgkmcnt(0)
	global_store_dwordx4 v[128:129], v[124:127], off
	v_pk_mul_f32 v[120:121], v[120:121], v[120:121]
	v_pk_mul_f32 v[118:119], v[118:119], v[118:119]
	v_pk_mul_f32 v[124:125], v[116:117], v[116:117]
	v_pk_mul_f32 v[116:117], v[114:115], v[114:115]
	v_cvt_pk_bf16_f32 v114, v118, v119
	v_cvt_pk_bf16_f32 v115, v120, v121
	v_cvt_pk_bf16_f32 v116, v116, v117
	v_cvt_pk_bf16_f32 v117, v124, v125
	ds_bpermute_b32 v114, v225, v114
	ds_bpermute_b32 v115, v225, v115
	ds_bpermute_b32 v116, v225, v116
	ds_bpermute_b32 v117, v225, v117
	s_waitcnt lgkmcnt(0)
	global_store_dwordx4 v[128:129], v[114:117], off offset:256
	v_pk_mul_f32 v[110:111], v[110:111], v[156:157] op_sel_hi:[1,0]
	v_pk_mul_f32 v[112:113], v[112:113], v[156:157] op_sel_hi:[1,0]
	v_or_b32_e32 v114, 16, v140
	v_ashrrev_i32_e32 v115, 31, v114
	v_max_f32_e32 v111, 0, v111
	v_max_f32_e32 v110, 0, v110
	v_pk_mul_f32 v[108:109], v[108:109], v[156:157] op_sel_hi:[1,0]
	v_pk_mul_f32 v[106:107], v[106:107], v[156:157] op_sel_hi:[1,0]
	v_lshlrev_b64 v[114:115], 13, v[114:115]
	v_max_f32_e32 v113, 0, v113
	v_max_f32_e32 v112, 0, v112
	v_max_f32_e32 v109, 0, v109
	v_max_f32_e32 v108, 0, v108
	v_max_f32_e32 v107, 0, v107
	v_max_f32_e32 v106, 0, v106
	v_pk_mul_f32 v[110:111], v[110:111], v[110:111]
	v_pk_mul_f32 v[112:113], v[112:113], v[112:113]
	v_pk_mul_f32 v[116:117], v[108:109], v[108:109]
	v_pk_mul_f32 v[108:109], v[106:107], v[106:107]
	v_cvt_pk_bf16_f32 v106, v110, v111
	v_lshl_add_u64 v[110:111], s[68:69], 0, v[114:115]
	v_pk_mul_f32 v[104:105], v[104:105], v[156:157] op_sel_hi:[1,0]
	v_pk_mul_f32 v[102:103], v[102:103], v[156:157] op_sel_hi:[1,0]
	v_pk_mul_f32 v[100:101], v[100:101], v[156:157] op_sel_hi:[1,0]
	v_pk_mul_f32 v[98:99], v[98:99], v[156:157] op_sel_hi:[1,0]
	v_cvt_pk_bf16_f32 v107, v112, v113
	v_cvt_pk_bf16_f32 v108, v108, v109
	v_cvt_pk_bf16_f32 v109, v116, v117
	v_lshl_add_u64 v[110:111], v[110:111], 0, v[122:123]
	v_max_f32_e32 v105, 0, v105
	v_max_f32_e32 v104, 0, v104
	v_max_f32_e32 v103, 0, v103
	v_max_f32_e32 v102, 0, v102
	v_max_f32_e32 v101, 0, v101
	v_max_f32_e32 v100, 0, v100
	v_max_f32_e32 v99, 0, v99
	v_max_f32_e32 v98, 0, v98
	v_lshl_add_u64 v[110:111], v[110:111], 0, v[222:223]
	ds_bpermute_b32 v106, v225, v106
	ds_bpermute_b32 v107, v225, v107
	ds_bpermute_b32 v108, v225, v108
	ds_bpermute_b32 v109, v225, v109
	s_waitcnt lgkmcnt(0)
	global_store_dwordx4 v[110:111], v[106:109], off
	v_pk_mul_f32 v[104:105], v[104:105], v[104:105]
	v_pk_mul_f32 v[102:103], v[102:103], v[102:103]
	v_pk_mul_f32 v[106:107], v[100:101], v[100:101]
	v_pk_mul_f32 v[100:101], v[98:99], v[98:99]
	v_cvt_pk_bf16_f32 v98, v102, v103
	v_cvt_pk_bf16_f32 v99, v104, v105
	v_cvt_pk_bf16_f32 v100, v100, v101
	v_cvt_pk_bf16_f32 v101, v106, v107
	ds_bpermute_b32 v98, v225, v98
	ds_bpermute_b32 v99, v225, v99
	ds_bpermute_b32 v100, v225, v100
	ds_bpermute_b32 v101, v225, v101
	s_waitcnt lgkmcnt(0)
	global_store_dwordx4 v[110:111], v[98:101], off offset:256
	v_pk_mul_f32 v[94:95], v[94:95], v[154:155] op_sel_hi:[1,0]
	v_pk_mul_f32 v[96:97], v[96:97], v[154:155] op_sel_hi:[1,0]
	v_or_b32_e32 v98, 32, v140
	v_ashrrev_i32_e32 v99, 31, v98
	v_max_f32_e32 v95, 0, v95
	v_max_f32_e32 v94, 0, v94
	v_pk_mul_f32 v[92:93], v[92:93], v[154:155] op_sel_hi:[1,0]
	v_pk_mul_f32 v[90:91], v[90:91], v[154:155] op_sel_hi:[1,0]
	v_lshlrev_b64 v[98:99], 13, v[98:99]
	v_max_f32_e32 v97, 0, v97
	v_max_f32_e32 v96, 0, v96
	v_max_f32_e32 v93, 0, v93
	v_max_f32_e32 v92, 0, v92
	v_max_f32_e32 v91, 0, v91
	v_max_f32_e32 v90, 0, v90
	v_pk_mul_f32 v[94:95], v[94:95], v[94:95]
	v_pk_mul_f32 v[96:97], v[96:97], v[96:97]
	v_pk_mul_f32 v[100:101], v[92:93], v[92:93]
	v_pk_mul_f32 v[92:93], v[90:91], v[90:91]
	v_cvt_pk_bf16_f32 v90, v94, v95
	v_lshl_add_u64 v[94:95], s[68:69], 0, v[98:99]
	v_pk_mul_f32 v[88:89], v[88:89], v[154:155] op_sel_hi:[1,0]
	v_pk_mul_f32 v[86:87], v[86:87], v[154:155] op_sel_hi:[1,0]
	v_pk_mul_f32 v[84:85], v[84:85], v[154:155] op_sel_hi:[1,0]
	v_pk_mul_f32 v[82:83], v[82:83], v[154:155] op_sel_hi:[1,0]
	v_cvt_pk_bf16_f32 v91, v96, v97
	v_cvt_pk_bf16_f32 v92, v92, v93
	v_cvt_pk_bf16_f32 v93, v100, v101
	v_lshl_add_u64 v[94:95], v[94:95], 0, v[122:123]
	v_max_f32_e32 v89, 0, v89
	v_max_f32_e32 v88, 0, v88
	v_max_f32_e32 v87, 0, v87
	v_max_f32_e32 v86, 0, v86
	v_max_f32_e32 v85, 0, v85
	v_max_f32_e32 v84, 0, v84
	v_max_f32_e32 v83, 0, v83
	v_max_f32_e32 v82, 0, v82
	v_lshl_add_u64 v[94:95], v[94:95], 0, v[222:223]
	ds_bpermute_b32 v90, v225, v90
	ds_bpermute_b32 v91, v225, v91
	ds_bpermute_b32 v92, v225, v92
	ds_bpermute_b32 v93, v225, v93
	s_waitcnt lgkmcnt(0)
	global_store_dwordx4 v[94:95], v[90:93], off
	v_pk_mul_f32 v[88:89], v[88:89], v[88:89]
	v_pk_mul_f32 v[86:87], v[86:87], v[86:87]
	v_pk_mul_f32 v[90:91], v[84:85], v[84:85]
	v_pk_mul_f32 v[84:85], v[82:83], v[82:83]
	v_cvt_pk_bf16_f32 v82, v86, v87
	v_cvt_pk_bf16_f32 v83, v88, v89
	v_cvt_pk_bf16_f32 v84, v84, v85
	v_cvt_pk_bf16_f32 v85, v90, v91
	ds_bpermute_b32 v82, v225, v82
	ds_bpermute_b32 v83, v225, v83
	ds_bpermute_b32 v84, v225, v84
	ds_bpermute_b32 v85, v225, v85
	s_waitcnt lgkmcnt(0)
	global_store_dwordx4 v[94:95], v[82:85], off offset:256
	v_pk_mul_f32 v[78:79], v[78:79], v[152:153] op_sel_hi:[1,0]
	v_pk_mul_f32 v[80:81], v[80:81], v[152:153] op_sel_hi:[1,0]
	v_or_b32_e32 v82, 48, v140
	v_ashrrev_i32_e32 v83, 31, v82
	v_max_f32_e32 v79, 0, v79
	v_max_f32_e32 v78, 0, v78
	v_pk_mul_f32 v[76:77], v[76:77], v[152:153] op_sel_hi:[1,0]
	v_pk_mul_f32 v[74:75], v[74:75], v[152:153] op_sel_hi:[1,0]
	v_lshlrev_b64 v[82:83], 13, v[82:83]
	v_max_f32_e32 v81, 0, v81
	v_max_f32_e32 v80, 0, v80
	v_max_f32_e32 v77, 0, v77
	v_max_f32_e32 v76, 0, v76
	v_max_f32_e32 v75, 0, v75
	v_max_f32_e32 v74, 0, v74
	v_pk_mul_f32 v[78:79], v[78:79], v[78:79]
	v_pk_mul_f32 v[80:81], v[80:81], v[80:81]
	v_pk_mul_f32 v[84:85], v[76:77], v[76:77]
	v_pk_mul_f32 v[76:77], v[74:75], v[74:75]
	v_cvt_pk_bf16_f32 v74, v78, v79
	v_lshl_add_u64 v[78:79], s[68:69], 0, v[82:83]
	v_pk_mul_f32 v[72:73], v[72:73], v[152:153] op_sel_hi:[1,0]
	v_pk_mul_f32 v[70:71], v[70:71], v[152:153] op_sel_hi:[1,0]
	v_pk_mul_f32 v[68:69], v[68:69], v[152:153] op_sel_hi:[1,0]
	v_pk_mul_f32 v[66:67], v[66:67], v[152:153] op_sel_hi:[1,0]
	v_cvt_pk_bf16_f32 v75, v80, v81
	v_cvt_pk_bf16_f32 v76, v76, v77
	v_cvt_pk_bf16_f32 v77, v84, v85
	v_lshl_add_u64 v[78:79], v[78:79], 0, v[122:123]
	v_max_f32_e32 v73, 0, v73
	v_max_f32_e32 v72, 0, v72
	v_max_f32_e32 v71, 0, v71
	v_max_f32_e32 v70, 0, v70
	v_max_f32_e32 v69, 0, v69
	v_max_f32_e32 v68, 0, v68
	v_max_f32_e32 v67, 0, v67
	v_max_f32_e32 v66, 0, v66
	v_lshl_add_u64 v[78:79], v[78:79], 0, v[222:223]
	ds_bpermute_b32 v74, v225, v74
	ds_bpermute_b32 v75, v225, v75
	ds_bpermute_b32 v76, v225, v76
	ds_bpermute_b32 v77, v225, v77
	s_waitcnt lgkmcnt(0)
	global_store_dwordx4 v[78:79], v[74:77], off
	v_pk_mul_f32 v[72:73], v[72:73], v[72:73]
	v_pk_mul_f32 v[70:71], v[70:71], v[70:71]
	v_pk_mul_f32 v[74:75], v[68:69], v[68:69]
	v_pk_mul_f32 v[68:69], v[66:67], v[66:67]
	v_cvt_pk_bf16_f32 v66, v70, v71
	v_cvt_pk_bf16_f32 v67, v72, v73
	v_cvt_pk_bf16_f32 v68, v68, v69
	v_cvt_pk_bf16_f32 v69, v74, v75
	ds_bpermute_b32 v66, v225, v66
	ds_bpermute_b32 v67, v225, v67
	ds_bpermute_b32 v68, v225, v68
	ds_bpermute_b32 v69, v225, v69
	s_waitcnt lgkmcnt(0)
	global_store_dwordx4 v[78:79], v[66:69], off offset:256
	v_pk_mul_f32 v[62:63], v[62:63], v[150:151] op_sel_hi:[1,0]
	v_ashrrev_i32_e32 v161, 31, v160
	v_pk_mul_f32 v[64:65], v[64:65], v[150:151] op_sel_hi:[1,0]
	v_max_f32_e32 v63, 0, v63
	v_max_f32_e32 v62, 0, v62
	v_pk_mul_f32 v[60:61], v[60:61], v[150:151] op_sel_hi:[1,0]
	v_pk_mul_f32 v[58:59], v[58:59], v[150:151] op_sel_hi:[1,0]
	v_lshlrev_b64 v[66:67], 13, v[160:161]
	v_max_f32_e32 v65, 0, v65
	v_max_f32_e32 v64, 0, v64
	v_max_f32_e32 v61, 0, v61
	v_max_f32_e32 v60, 0, v60
	v_max_f32_e32 v59, 0, v59
	v_max_f32_e32 v58, 0, v58
	v_pk_mul_f32 v[62:63], v[62:63], v[62:63]
	v_pk_mul_f32 v[64:65], v[64:65], v[64:65]
	v_pk_mul_f32 v[68:69], v[60:61], v[60:61]
	v_pk_mul_f32 v[60:61], v[58:59], v[58:59]
	v_cvt_pk_bf16_f32 v58, v62, v63
	v_lshl_add_u64 v[62:63], s[68:69], 0, v[66:67]
	v_pk_mul_f32 v[56:57], v[56:57], v[150:151] op_sel_hi:[1,0]
	v_pk_mul_f32 v[54:55], v[54:55], v[150:151] op_sel_hi:[1,0]
	v_pk_mul_f32 v[52:53], v[52:53], v[150:151] op_sel_hi:[1,0]
	v_pk_mul_f32 v[50:51], v[50:51], v[150:151] op_sel_hi:[1,0]
	v_cvt_pk_bf16_f32 v59, v64, v65
	v_cvt_pk_bf16_f32 v60, v60, v61
	v_cvt_pk_bf16_f32 v61, v68, v69
	v_lshl_add_u64 v[62:63], v[62:63], 0, v[122:123]
	v_max_f32_e32 v57, 0, v57
	v_max_f32_e32 v56, 0, v56
	v_max_f32_e32 v55, 0, v55
	v_max_f32_e32 v54, 0, v54
	v_max_f32_e32 v53, 0, v53
	v_max_f32_e32 v52, 0, v52
	v_max_f32_e32 v51, 0, v51
	v_max_f32_e32 v50, 0, v50
	v_lshl_add_u64 v[62:63], v[62:63], 0, v[222:223]
	ds_bpermute_b32 v58, v225, v58
	ds_bpermute_b32 v59, v225, v59
	ds_bpermute_b32 v60, v225, v60
	ds_bpermute_b32 v61, v225, v61
	s_waitcnt lgkmcnt(0)
	global_store_dwordx4 v[62:63], v[58:61], off
	v_pk_mul_f32 v[56:57], v[56:57], v[56:57]
	v_pk_mul_f32 v[54:55], v[54:55], v[54:55]
	v_pk_mul_f32 v[58:59], v[52:53], v[52:53]
	v_pk_mul_f32 v[52:53], v[50:51], v[50:51]
	v_cvt_pk_bf16_f32 v50, v54, v55
	v_cvt_pk_bf16_f32 v51, v56, v57
	v_cvt_pk_bf16_f32 v52, v52, v53
	v_cvt_pk_bf16_f32 v53, v58, v59
	ds_bpermute_b32 v50, v225, v50
	ds_bpermute_b32 v51, v225, v51
	ds_bpermute_b32 v52, v225, v52
	ds_bpermute_b32 v53, v225, v53
	s_waitcnt lgkmcnt(0)
	global_store_dwordx4 v[62:63], v[50:53], off offset:256
	v_pk_mul_f32 v[46:47], v[46:47], v[148:149] op_sel_hi:[1,0]
	v_pk_mul_f32 v[48:49], v[48:49], v[148:149] op_sel_hi:[1,0]
	v_add_u32_e32 v50, 0x90, v140
	v_ashrrev_i32_e32 v51, 31, v50
	v_max_f32_e32 v47, 0, v47
	v_max_f32_e32 v46, 0, v46
	v_pk_mul_f32 v[44:45], v[44:45], v[148:149] op_sel_hi:[1,0]
	v_pk_mul_f32 v[42:43], v[42:43], v[148:149] op_sel_hi:[1,0]
	v_lshlrev_b64 v[50:51], 13, v[50:51]
	v_max_f32_e32 v49, 0, v49
	v_max_f32_e32 v48, 0, v48
	v_max_f32_e32 v45, 0, v45
	v_max_f32_e32 v44, 0, v44
	v_max_f32_e32 v43, 0, v43
	v_max_f32_e32 v42, 0, v42
	v_pk_mul_f32 v[46:47], v[46:47], v[46:47]
	v_pk_mul_f32 v[48:49], v[48:49], v[48:49]
	v_pk_mul_f32 v[52:53], v[44:45], v[44:45]
	v_pk_mul_f32 v[44:45], v[42:43], v[42:43]
	v_cvt_pk_bf16_f32 v42, v46, v47
	v_lshl_add_u64 v[46:47], s[68:69], 0, v[50:51]
	v_pk_mul_f32 v[40:41], v[40:41], v[148:149] op_sel_hi:[1,0]
	v_pk_mul_f32 v[38:39], v[38:39], v[148:149] op_sel_hi:[1,0]
	v_pk_mul_f32 v[36:37], v[36:37], v[148:149] op_sel_hi:[1,0]
	v_pk_mul_f32 v[34:35], v[34:35], v[148:149] op_sel_hi:[1,0]
	v_cvt_pk_bf16_f32 v43, v48, v49
	v_cvt_pk_bf16_f32 v44, v44, v45
	v_cvt_pk_bf16_f32 v45, v52, v53
	v_lshl_add_u64 v[46:47], v[46:47], 0, v[122:123]
	v_max_f32_e32 v41, 0, v41
	v_max_f32_e32 v40, 0, v40
	v_max_f32_e32 v39, 0, v39
	v_max_f32_e32 v38, 0, v38
	v_max_f32_e32 v37, 0, v37
	v_max_f32_e32 v36, 0, v36
	v_max_f32_e32 v35, 0, v35
	v_max_f32_e32 v34, 0, v34
	v_lshl_add_u64 v[46:47], v[46:47], 0, v[222:223]
	ds_bpermute_b32 v42, v225, v42
	ds_bpermute_b32 v43, v225, v43
	ds_bpermute_b32 v44, v225, v44
	ds_bpermute_b32 v45, v225, v45
	s_waitcnt lgkmcnt(0)
	global_store_dwordx4 v[46:47], v[42:45], off
	v_pk_mul_f32 v[40:41], v[40:41], v[40:41]
	v_pk_mul_f32 v[38:39], v[38:39], v[38:39]
	v_pk_mul_f32 v[42:43], v[36:37], v[36:37]
	v_pk_mul_f32 v[36:37], v[34:35], v[34:35]
	v_cvt_pk_bf16_f32 v34, v38, v39
	v_cvt_pk_bf16_f32 v35, v40, v41
	v_cvt_pk_bf16_f32 v36, v36, v37
	v_cvt_pk_bf16_f32 v37, v42, v43
	ds_bpermute_b32 v34, v225, v34
	ds_bpermute_b32 v35, v225, v35
	ds_bpermute_b32 v36, v225, v36
	ds_bpermute_b32 v37, v225, v37
	s_waitcnt lgkmcnt(0)
	global_store_dwordx4 v[46:47], v[34:37], off offset:256
	v_pk_mul_f32 v[30:31], v[30:31], v[146:147] op_sel_hi:[1,0]
	v_pk_mul_f32 v[32:33], v[32:33], v[146:147] op_sel_hi:[1,0]
	v_add_u32_e32 v34, 0xa0, v140
	v_ashrrev_i32_e32 v35, 31, v34
	v_max_f32_e32 v31, 0, v31
	v_max_f32_e32 v30, 0, v30
	v_pk_mul_f32 v[28:29], v[28:29], v[146:147] op_sel_hi:[1,0]
	v_pk_mul_f32 v[26:27], v[26:27], v[146:147] op_sel_hi:[1,0]
	v_lshlrev_b64 v[34:35], 13, v[34:35]
	v_max_f32_e32 v33, 0, v33
	v_max_f32_e32 v32, 0, v32
	v_max_f32_e32 v29, 0, v29
	v_max_f32_e32 v28, 0, v28
	v_max_f32_e32 v27, 0, v27
	v_max_f32_e32 v26, 0, v26
	v_pk_mul_f32 v[30:31], v[30:31], v[30:31]
	v_pk_mul_f32 v[32:33], v[32:33], v[32:33]
	v_pk_mul_f32 v[36:37], v[28:29], v[28:29]
	v_pk_mul_f32 v[28:29], v[26:27], v[26:27]
	v_cvt_pk_bf16_f32 v26, v30, v31
	v_lshl_add_u64 v[30:31], s[68:69], 0, v[34:35]
	v_pk_mul_f32 v[24:25], v[24:25], v[146:147] op_sel_hi:[1,0]
	v_pk_mul_f32 v[22:23], v[22:23], v[146:147] op_sel_hi:[1,0]
	v_pk_mul_f32 v[20:21], v[20:21], v[146:147] op_sel_hi:[1,0]
	v_pk_mul_f32 v[18:19], v[18:19], v[146:147] op_sel_hi:[1,0]
	v_cvt_pk_bf16_f32 v27, v32, v33
	v_cvt_pk_bf16_f32 v28, v28, v29
	v_cvt_pk_bf16_f32 v29, v36, v37
	v_lshl_add_u64 v[30:31], v[30:31], 0, v[122:123]
	v_max_f32_e32 v25, 0, v25
	v_max_f32_e32 v24, 0, v24
	v_max_f32_e32 v23, 0, v23
	v_max_f32_e32 v22, 0, v22
	v_max_f32_e32 v21, 0, v21
	v_max_f32_e32 v20, 0, v20
	v_max_f32_e32 v19, 0, v19
	v_max_f32_e32 v18, 0, v18
	v_lshl_add_u64 v[30:31], v[30:31], 0, v[222:223]
	ds_bpermute_b32 v26, v225, v26
	ds_bpermute_b32 v27, v225, v27
	ds_bpermute_b32 v28, v225, v28
	ds_bpermute_b32 v29, v225, v29
	s_waitcnt lgkmcnt(0)
	global_store_dwordx4 v[30:31], v[26:29], off
	v_pk_mul_f32 v[24:25], v[24:25], v[24:25]
	v_pk_mul_f32 v[22:23], v[22:23], v[22:23]
	v_pk_mul_f32 v[26:27], v[20:21], v[20:21]
	v_pk_mul_f32 v[20:21], v[18:19], v[18:19]
	v_pk_mul_f32 v[14:15], v[14:15], v[142:143] op_sel_hi:[1,0]
	v_cvt_pk_bf16_f32 v18, v22, v23
	v_cvt_pk_bf16_f32 v19, v24, v25
	v_cvt_pk_bf16_f32 v20, v20, v21
	v_cvt_pk_bf16_f32 v21, v26, v27
	v_pk_mul_f32 v[16:17], v[16:17], v[142:143] op_sel_hi:[1,0]
	v_max_f32_e32 v15, 0, v15
	v_max_f32_e32 v14, 0, v14
	v_pk_mul_f32 v[12:13], v[12:13], v[142:143] op_sel_hi:[1,0]
	v_pk_mul_f32 v[10:11], v[10:11], v[142:143] op_sel_hi:[1,0]
	ds_bpermute_b32 v18, v225, v18
	ds_bpermute_b32 v19, v225, v19
	ds_bpermute_b32 v20, v225, v20
	ds_bpermute_b32 v21, v225, v21
	s_waitcnt lgkmcnt(0)
	global_store_dwordx4 v[30:31], v[18:21], off offset:256
	v_max_f32_e32 v17, 0, v17
	v_max_f32_e32 v16, 0, v16
	v_lshlrev_b64 v[18:19], 13, v[144:145]
	v_max_f32_e32 v13, 0, v13
	v_max_f32_e32 v12, 0, v12
	v_max_f32_e32 v11, 0, v11
	v_max_f32_e32 v10, 0, v10
	v_pk_mul_f32 v[14:15], v[14:15], v[14:15]
	v_pk_mul_f32 v[16:17], v[16:17], v[16:17]
	v_pk_mul_f32 v[20:21], v[12:13], v[12:13]
	v_pk_mul_f32 v[12:13], v[10:11], v[10:11]
	v_cvt_pk_bf16_f32 v10, v14, v15
	v_lshl_add_u64 v[14:15], s[68:69], 0, v[18:19]
	v_pk_mul_f32 v[8:9], v[8:9], v[142:143] op_sel_hi:[1,0]
	v_pk_mul_f32 v[6:7], v[6:7], v[142:143] op_sel_hi:[1,0]
	v_pk_mul_f32 v[4:5], v[4:5], v[142:143] op_sel_hi:[1,0]
	v_pk_mul_f32 v[2:3], v[2:3], v[142:143] op_sel_hi:[1,0]
	v_cvt_pk_bf16_f32 v11, v16, v17
	v_cvt_pk_bf16_f32 v12, v12, v13
	v_cvt_pk_bf16_f32 v13, v20, v21
	v_lshl_add_u64 v[14:15], v[14:15], 0, v[122:123]
	v_max_f32_e32 v9, 0, v9
	v_max_f32_e32 v8, 0, v8
	v_max_f32_e32 v7, 0, v7
	v_max_f32_e32 v6, 0, v6
	v_max_f32_e32 v5, 0, v5
	v_max_f32_e32 v4, 0, v4
	v_max_f32_e32 v3, 0, v3
	v_max_f32_e32 v2, 0, v2
	v_lshl_add_u64 v[14:15], v[14:15], 0, v[222:223]
	ds_bpermute_b32 v10, v225, v10
	ds_bpermute_b32 v11, v225, v11
	ds_bpermute_b32 v12, v225, v12
	ds_bpermute_b32 v13, v225, v13
	s_waitcnt lgkmcnt(0)
	global_store_dwordx4 v[14:15], v[10:13], off
	v_pk_mul_f32 v[8:9], v[8:9], v[8:9]
	v_pk_mul_f32 v[6:7], v[6:7], v[6:7]
	v_pk_mul_f32 v[10:11], v[4:5], v[4:5]
	v_pk_mul_f32 v[4:5], v[2:3], v[2:3]
	v_cvt_pk_bf16_f32 v2, v6, v7
	v_cvt_pk_bf16_f32 v3, v8, v9
	v_cvt_pk_bf16_f32 v4, v4, v5
	v_cvt_pk_bf16_f32 v5, v10, v11
	s_andn2_b64 vcc, exec, s[0:1]
	s_mov_b64 s[0:1], -1
	ds_bpermute_b32 v2, v225, v2
	ds_bpermute_b32 v3, v225, v3
	ds_bpermute_b32 v4, v225, v4
	ds_bpermute_b32 v5, v225, v5
	s_waitcnt lgkmcnt(0)
	global_store_dwordx4 v[14:15], v[2:5], off offset:256
	s_cbranch_vccnz .LBB0_842
	s_andn2_b64 vcc, exec, s[38:39]
	s_cbranch_vccnz .LBB0_841
	s_barrier
	s_branch .LBB0_841
